# speedup vs baseline: 1.0060x; 1.0060x over previous
; DI int my_tid() { int t = threadIdx.x; asm volatile("" : "+v"(t)); return t; }
; DI int my_block() { int b = blockIdx.x; asm volatile("" : "+s"(b)); return b; }
; #define G_WAIT_V(n) asm volatile("s_waitcnt vmcnt(" #n ")" ::: "memory")
; #define G_BAR __builtin_amdgcn_s_barrier()
;   DI int brow_of(int R) const { return (R & ~31) + perm32(R & 31); }
; template <class J>
; DI void gemm_phase(LAS unsigned char* lds, const J& job) {
;   const int tid = my_tid(), wid = __builtin_amdgcn_readfirstlane(tid >> 6), lane = tid & 63, wr = wid >> 2, wc = wid & 3, fr = lane & 15, fq = lane >> 4;
;   const int nt = job.nt;
;   unsigned voffA[2], voffB[2];
; #pragma unroll
;   for (int i = 0; i < 2; ++i) { int R, C; stage_rc(tid * 16 + i * 8192, R, C); const int Rb = job.brow_of(R);
;     voffA[i] = (unsigned)(R * job.lda + C) * 2u; voffB[i] = (unsigned)(Rb * job.ldb + C) * 2u; }
;   const size_t kstep = (size_t)(BK * 2);
;   const size_t hstepA = (size_t)HALF * job.lda * 2, hstepB = (size_t)job.bhalf_rows() * job.ldb * 2;
;   const unsigned ldsw = (unsigned)wid * 1024u;
;   const int aoff = lds_byte(wr * 64 + fr, fq * 8), boff = lds_byte(wc * 32 + fr, fq * 8);
;     ...
;   Unit cur, nxt; int ui = 0;
;   if (!job.next(0, cur)) return;
;   f32x4 acc[2][2][4][2];
; #pragma unroll
;   for (int a = 0; a < 2; ++a)
; #pragma unroll
;     for (int b = 0; b < 2; ++b)
; #pragma unroll
;       for (int m = 0; m < 4; ++m)
; #pragma unroll
;         for (int n = 0; n < 2; ++n) acc[a][b][m][n] = (f32x4){0.f, 0.f, 0.f, 0.f};
;   bf16x8 At[4][2], B0[2][2], B1[2][2];
;   const char* cA = job.aptr(cur); const char* cB = job.bptr(cur);
;   const int koff = (my_block() & 7) * (nt >> 3), kmask = nt - 1;
;     ...
;   G_STAGE(G_SB(0, 0), cB + G_KT(0), voffB); G_STAGE(G_SA(0, 0), cA + G_KT(0), voffA); G_STAGE(G_SB(0, 1), cB + hstepB + G_KT(0), voffB); G_STAGE(G_SA(0, 1), cA + hstepA + G_KT(0), voffA);
;   if (wr == 1) G_BAR;
;   G_WAIT_V(4); G_BAR;
;   G_STAGE(G_SB(1, 0), cB + G_KT(1), voffB); G_STAGE(G_SA(1, 0), cA + G_KT(1), voffA); G_STAGE(G_SB(1, 1), cB + hstepB + G_KT(1), voffB);
;   G_WAIT_V(6); G_BAR;
;     u.pn = ((((u.pn >> 2) + (c & 1)) & 1) << 2) + (u.pn & 3);
;     return true; }
;   DI const char* aptr(const Unit& u) const { return (const char*)(mixed + (size_t)u.pm * 256 * DM); }
;   DI const char* bptr(const Unit& u) const { return (const char*)(woutT + (size_t)u.pn * 256 * DM); }
.LBB0_32:
	v_bfe_i32 v3, v0, 27, 1
	v_lshlrev_b32_e32 v1, 4, v0
	v_lshrrev_b32_e32 v3, 22, v3
	v_writelane_b32 v255, s87, 22
	v_add_u32_e32 v3, v1, v3
	s_add_i32 s0, s4, s7
	s_ashr_i32 s5, s1, 8
	v_and_b32_e32 v3, 0xfffffc00, v3
	v_writelane_b32 v255, s1, 23
	s_ashr_i32 s6, s1, 6
	s_ashr_i32 s1, s0, 31
	v_ashrrev_i32_e32 v2, 31, v0
	v_sub_u32_e32 v3, v1, v3
	s_lshr_b32 s1, s1, 26
	v_lshrrev_b32_e32 v2, 26, v2
	s_waitcnt vmcnt(0)
	v_lshrrev_b32_e32 v4, 4, v3
	s_add_i32 s1, s0, s1
	v_add_u32_e32 v2, v0, v2
	v_bitop3_b32 v4, v4, v3, 32 bitop3:0x6c
	v_ashrrev_i32_e32 v3, 31, v3
	s_ashr_i32 s4, s1, 6
	s_and_b32 s1, s1, 0xffc0
	v_ashrrev_i32_e32 v2, 6, v2
	v_lshrrev_b32_e32 v3, 26, v3
	s_sub_i32 s0, s0, s1
	v_lshlrev_b32_e32 v5, 3, v2
	v_add_u32_e32 v3, v4, v3
	s_bfe_i32 s1, s0, 0x80000
	v_and_b32_e32 v5, -16, v5
	v_ashrrev_i32_e32 v3, 6, v3
	s_bfe_u32 s1, s1, 0x3000c
	v_add_u32_e32 v5, v3, v5
	v_mul_i32_i24_e32 v3, 64, v3
	s_add_i32 s1, s0, s1
	v_sub_u32_e32 v3, v4, v3
	s_lshl_b32 s15, s4, 3
	s_bfe_i32 s4, s1, 0x80000
	s_and_b32 s1, s1, 0xf8
	v_lshlrev_b32_e32 v2, 5, v2
	v_ashrrev_i16_sdwa v3, v220, sext(v3) dst_sel:DWORD dst_unused:UNUSED_PAD src0_sel:DWORD src1_sel:BYTE_0
	v_lshlrev_b32_e32 v4, 1, v5
	v_lshrrev_b32_e32 v6, 2, v5
	s_sub_i32 s0, s0, s1
	v_and_b32_e32 v2, 32, v2
	v_bfe_i32 v3, v3, 0, 16
	v_and_b32_e32 v4, 24, v4
	v_and_b32_e32 v6, 4, v6
	v_and_b32_e32 v7, 0xfffe3, v5
	s_and_b32 s4, 0xffff, s4
	s_sext_i32_i8 s0, s0
	v_or3_b32 v4, v7, v6, v4
	v_add_lshl_u32 v2, v2, v3, 1
	v_add_u32_e32 v1, 0x2000, v1
	s_lshr_b32 s7, s4, 3
	s_add_i32 s66, s15, s0
	s_lshl_b32 s15, s43, 2
	v_lshl_add_u32 v148, v5, 12, v2
	v_lshl_add_u32 v146, v4, 12, v2
	v_ashrrev_i32_e32 v2, 31, v1
	s_add_i32 s0, s15, s7
	v_lshrrev_b32_e32 v2, 22, v2
	s_and_b32 s0, s0, 4
	s_bfe_u32 s1, s4, 0x20003
	v_add_u32_e32 v2, v1, v2
	s_or_b32 s46, s0, s1
	s_ashr_i32 s67, s66, 31
	v_ashrrev_i32_e32 v2, 10, v2
	s_lshl_b32 s14, s6, 10
	s_lshl_b64 s[0:1], s[66:67], 20
	s_lshl_b32 s4, s46, 20
	v_mul_i32_i24_e32 v3, 0x400, v2
	s_add_u32 s68, s12, s4
	s_mov_b32 s4, s2
	v_sub_u32_e32 v1, v1, v3
	s_addc_u32 s69, s13, 0
	s_lshl_b32 s2, s4, 2
	v_lshrrev_b32_e32 v3, 4, v1
	s_and_b32 s2, s2, 28
	v_bitop3_b32 v1, v3, v1, 32 bitop3:0x6c
	s_lshl_b32 s24, s2, 7
	v_ashrrev_i32_e32 v4, 31, v1
	s_add_u32 s18, s68, s24
	v_lshrrev_b32_e32 v4, 26, v4
	s_addc_u32 s19, s69, 0
	s_add_i32 s25, s14, 0x100
	v_lshlrev_b32_e32 v3, 3, v2
	v_add_u32_e32 v4, v1, v4
	s_add_i32 m0, s25, 0x10000
	v_and_b32_e32 v3, -16, v3
	v_ashrrev_i32_e32 v5, 6, v4
	v_and_b32_e32 v4, 0xc0, v4
	global_load_lds_dwordx4 v146, s[18:19]
	s_add_i32 m0, s25, 0x12000
	v_add_u32_e32 v3, v5, v3
	v_sub_u32_e32 v1, v1, v4
	s_add_u32 s70, s10, s0
	v_lshlrev_b32_e32 v2, 5, v2
	v_ashrrev_i16_sdwa v1, v220, sext(v1) dst_sel:DWORD dst_unused:UNUSED_PAD src0_sel:DWORD src1_sel:BYTE_0
	v_lshlrev_b32_e32 v4, 1, v3
	v_lshrrev_b32_e32 v5, 2, v3
	s_addc_u32 s71, s11, s1
	v_and_b32_e32 v2, 32, v2
	v_bfe_i32 v1, v1, 0, 16
	v_and_b32_e32 v4, 24, v4
	v_and_b32_e32 v5, 4, v5
	v_and_b32_e32 v6, 0xfffe3, v3
	s_add_u32 s0, s70, s24
	v_or3_b32 v4, v6, v5, v4
	v_add_lshl_u32 v1, v2, v1, 1
	s_addc_u32 s1, s71, 0
	s_add_i32 s36, s25, 0x2000
	v_lshl_add_u32 v152, v4, 12, v1
	s_add_u32 s7, s68, 0x80000
	global_load_lds_dwordx4 v152, s[18:19]
	s_mov_b32 m0, s25
	s_addc_u32 s18, s69, 0
	v_lshl_add_u32 v150, v3, 12, v1
	global_load_lds_dwordx4 v148, s[0:1]
	s_mov_b32 m0, s36
	s_add_u32 s20, s7, s24
	global_load_lds_dwordx4 v150, s[0:1]
	s_addc_u32 s21, s18, 0
	s_add_i32 m0, s25, 0x14000
	s_nop 0
	global_load_lds_dwordx4 v146, s[20:21]
	s_add_i32 m0, s25, 0x16000
	s_add_u32 s0, s0, 0x80000
	s_addc_u32 s1, s1, 0
	s_add_i32 s37, s25, 0x4000
	global_load_lds_dwordx4 v152, s[20:21]
	s_mov_b32 m0, s37
	s_add_i32 s38, s25, 0x6000
	global_load_lds_dwordx4 v148, s[0:1]
	s_mov_b32 m0, s38
	s_setprio 1
	s_cmp_lg_u32 s5, 1
	global_load_lds_dwordx4 v150, s[0:1]
	s_cbranch_scc1 .LBB0_34
	s_barrier
	s_setprio 0

; DI int my_tid() { int t = threadIdx.x; asm volatile("" : "+v"(t)); return t; }
; DI int my_block() { int b = blockIdx.x; asm volatile("" : "+s"(b)); return b; }
; #define G_WAIT_V(n) asm volatile("s_waitcnt vmcnt(" #n ")" ::: "memory")
; #define G_BAR __builtin_amdgcn_s_barrier()
; template <class J>
; DI void gemm_phase(LAS unsigned char* lds, const J& job) {
;   const int tid = my_tid(), wid = __builtin_amdgcn_readfirstlane(tid >> 6), lane = tid & 63, wr = wid >> 2, wc = wid & 3, fr = lane & 15, fq = lane >> 4;
;   const int nt = job.nt;
;   unsigned voffA[2], voffB[2];
; #pragma unroll
;   for (int i = 0; i < 2; ++i) { int R, C; stage_rc(tid * 16 + i * 8192, R, C); const int Rb = job.brow_of(R);
;     voffA[i] = (unsigned)(R * job.lda + C) * 2u; voffB[i] = (unsigned)(Rb * job.ldb + C) * 2u; }
;   const size_t kstep = (size_t)(BK * 2);
;   const size_t hstepA = (size_t)HALF * job.lda * 2, hstepB = (size_t)job.bhalf_rows() * job.ldb * 2;
;   const unsigned ldsw = (unsigned)wid * 1024u;
;   const int aoff = lds_byte(wr * 64 + fr, fq * 8), boff = lds_byte(wc * 32 + fr, fq * 8);
;     ...
;   Unit cur, nxt; int ui = 0;
;   if (!job.next(0, cur)) return;
;   f32x4 acc[2][2][4][2];
; #pragma unroll
;   for (int a = 0; a < 2; ++a)
; #pragma unroll
;     for (int b = 0; b < 2; ++b)
; #pragma unroll
;       for (int m = 0; m < 4; ++m)
; #pragma unroll
;         for (int n = 0; n < 2; ++n) acc[a][b][m][n] = (f32x4){0.f, 0.f, 0.f, 0.f};
;   bf16x8 At[4][2], B0[2][2], B1[2][2];
;   const char* cA = job.aptr(cur); const char* cB = job.bptr(cur);
;   const int koff = (my_block() & 7) * (nt >> 3), kmask = nt - 1;
;     ...
;   G_STAGE(G_SB(0, 0), cB + G_KT(0), voffB); G_STAGE(G_SA(0, 0), cA + G_KT(0), voffA); G_STAGE(G_SB(0, 1), cB + hstepB + G_KT(0), voffB); G_STAGE(G_SA(0, 1), cA + hstepA + G_KT(0), voffA);
;   if (wr == 1) G_BAR;
;   G_WAIT_V(4); G_BAR;
;   G_STAGE(G_SB(1, 0), cB + G_KT(1), voffB); G_STAGE(G_SA(1, 0), cA + G_KT(1), voffA); G_STAGE(G_SB(1, 1), cB + hstepB + G_KT(1), voffB);
;   G_WAIT_V(6); G_BAR;
;   DI int brow_of(int R) const { return ((R >> 4) & 1) * 2048 + 16 * (R >> 5) + (R & 15); }
;     u.pn = ((((u.pn >> 2) + (c & 7)) & 7) << 2) + (u.pn & 3);
;     return true; }
;   DI const char* aptr(const Unit& u) const { return (const char*)(h + (size_t)u.pm * 256 * DM); }
;   DI const char* bptr(const Unit& u) const { return (const char*)(wgT + (size_t)u.pn * 64 * DM); }
.LBB0_64:
	v_bfe_i32 v3, v0, 27, 1
	v_lshlrev_b32_e32 v1, 4, v0
	v_lshrrev_b32_e32 v3, 22, v3
	v_add_u32_e32 v3, v1, v3
	v_and_b32_e32 v3, 0xfffffc00, v3
	v_ashrrev_i32_e32 v2, 31, v0
	v_sub_u32_e32 v3, v1, v3
	v_lshrrev_b32_e32 v2, 26, v2
	s_waitcnt vmcnt(0)
	v_lshrrev_b32_e32 v4, 4, v3
	v_add_u32_e32 v2, v0, v2
	v_bitop3_b32 v4, v4, v3, 32 bitop3:0x6c
	v_ashrrev_i32_e32 v3, 31, v3
	s_ashr_i32 s0, s5, 3
	v_writelane_b32 v255, s87, 22
	v_ashrrev_i32_e32 v2, 6, v2
	v_lshrrev_b32_e32 v3, 26, v3
	s_add_i32 s0, s7, s0
	s_ashr_i32 s4, s1, 6
	v_lshlrev_b32_e32 v5, 3, v2
	v_add_u32_e32 v3, v4, v3
	v_writelane_b32 v255, s1, 23
	s_ashr_i32 s6, s1, 8
	s_ashr_i32 s1, s0, 31
	v_and_b32_e32 v5, -16, v5
	v_ashrrev_i32_e32 v3, 6, v3
	s_lshr_b32 s1, s1, 24
	v_add_u32_e32 v5, v3, v5
	v_mul_i32_i24_e32 v6, 64, v3
	s_add_i32 s1, s0, s1
	v_sub_u32_e32 v4, v4, v6
	v_lshlrev_b32_e32 v6, 7, v5
	v_lshrrev_b32_e32 v7, 1, v5
	s_ashr_i32 s5, s1, 8
	s_and_b32 s1, s1, 0xffffff00
	v_lshlrev_b32_e32 v2, 5, v2
	v_ashrrev_i16_sdwa v4, v220, sext(v4) dst_sel:DWORD dst_unused:UNUSED_PAD src0_sel:DWORD src1_sel:BYTE_0
	v_and_b32_e32 v6, 0x800, v6
	v_and_b32_e32 v7, 0xffff0, v7
	s_sub_i32 s0, s0, s1
	v_and_b32_e32 v2, 32, v2
	v_bfe_i32 v4, v4, 0, 16
	v_add_u32_e32 v6, v6, v7
	s_sext_i32_i16 s1, s0
	v_and_or_b32 v3, v3, 15, v6
	v_add_lshl_u32 v2, v2, v4, 1
	v_add_u32_e32 v1, 0x2000, v1
	s_bfe_u32 s1, s1, 0x3001c
	v_lshl_add_u32 v148, v5, 12, v2
	v_lshl_add_u32 v146, v3, 12, v2
	v_ashrrev_i32_e32 v2, 31, v1
	s_add_i32 s1, s0, s1
	v_lshrrev_b32_e32 v2, 22, v2
	s_sext_i32_i16 s7, s1
	s_and_b32 s1, s1, 0xfff8
	v_add_u32_e32 v2, v1, v2
	s_sub_i32 s0, s0, s1
	v_ashrrev_i32_e32 v2, 10, v2
	s_lshl_b32 s5, s5, 3
	s_lshr_b32 s8, s7, 3
	s_sext_i32_i16 s0, s0
	s_lshl_b32 s79, s43, 2
	v_mul_i32_i24_e32 v3, 0x400, v2
	s_add_i32 s64, s5, s0
	s_add_i32 s0, s79, s8
	v_sub_u32_e32 v1, v1, v3
	s_and_b32 s0, s0, 28
	s_bfe_u32 s1, s7, 0x20003
	v_lshrrev_b32_e32 v3, 4, v1
	s_or_b32 s44, s0, s1
	s_ashr_i32 s65, s64, 31
	v_bitop3_b32 v1, v3, v1, 32 bitop3:0x6c
	s_lshl_b32 s78, s4, 10
	s_lshl_b64 s[8:9], s[64:65], 20
	s_lshl_b32 s0, s44, 18
	v_ashrrev_i32_e32 v4, 31, v1
	s_add_u32 s66, s16, s0
	s_mov_b32 s5, s2
	v_lshrrev_b32_e32 v4, 26, v4
	s_addc_u32 s67, s17, 0
	s_lshl_b32 s0, s5, 2
	v_lshlrev_b32_e32 v3, 3, v2
	v_add_u32_e32 v4, v1, v4
	s_and_b32 s0, s0, 28
	v_and_b32_e32 v3, -16, v3
	v_ashrrev_i32_e32 v5, 6, v4
	s_lshl_b32 s65, s0, 7
	v_add_u32_e32 v3, v5, v3
	v_and_b32_e32 v4, 0xc0, v4
	s_add_u32 s18, s66, s65
	v_sub_u32_e32 v1, v1, v4
	v_lshlrev_b32_e32 v4, 7, v3
	v_lshrrev_b32_e32 v6, 1, v3
	s_addc_u32 s19, s67, 0
	s_add_i32 s14, s78, 0x100
	v_lshlrev_b32_e32 v2, 5, v2
	v_ashrrev_i16_sdwa v1, v220, sext(v1) dst_sel:DWORD dst_unused:UNUSED_PAD src0_sel:DWORD src1_sel:BYTE_0
	v_and_b32_e32 v4, 0x800, v4
	v_and_b32_e32 v6, 0xffff0, v6
	s_add_i32 m0, s14, 0x10000
	v_and_b32_e32 v2, 32, v2
	v_bfe_i32 v1, v1, 0, 16
	v_add_u32_e32 v4, v4, v6
	global_load_lds_dwordx4 v146, s[18:19]
	s_add_i32 m0, s14, 0x12000
	v_and_or_b32 v4, v5, 15, v4
	v_add_lshl_u32 v1, v2, v1, 1
	s_add_u32 s68, s58, s8
	v_lshl_add_u32 v152, v4, 12, v1
	s_addc_u32 s69, s59, s9
	global_load_lds_dwordx4 v152, s[18:19]
	s_add_u32 s18, s68, s65
	s_addc_u32 s19, s69, 0
	s_add_i32 s15, s14, 0x2000
	s_add_u32 s7, s66, 0x1000000
	s_mov_b32 m0, s14
	s_addc_u32 s8, s67, 0
	v_lshl_add_u32 v150, v3, 12, v1
	global_load_lds_dwordx4 v148, s[18:19]
	s_mov_b32 m0, s15
	s_add_u32 s20, s7, s65
	global_load_lds_dwordx4 v150, s[18:19]
	s_addc_u32 s21, s8, 0
	s_add_i32 m0, s14, 0x14000
	v_mov_b32_e32 v245, 0x2000
	global_load_lds_dwordx4 v146, s[20:21]
	s_add_i32 m0, s14, 0x16000
	s_add_u32 s18, s18, 0x80000
	s_addc_u32 s19, s19, 0
	s_add_i32 s83, s14, 0x4000
	global_load_lds_dwordx4 v152, s[20:21]
	s_mov_b32 m0, s83
	s_add_i32 s36, s14, 0x6000
	global_load_lds_dwordx4 v148, s[18:19]
	s_mov_b32 m0, s36
	v_mov_b32_e32 v254, 1
	global_load_lds_dwordx4 v150, s[18:19]
	s_setprio 1
	s_cmp_lg_u32 s6, 1
	s_cbranch_scc1 .LBB0_66
	s_barrier
	s_setprio 0

; DI int my_tid() { int t = threadIdx.x; asm volatile("" : "+v"(t)); return t; }
; DI int my_block() { int b = blockIdx.x; asm volatile("" : "+s"(b)); return b; }
; #define G_STAGE(bufoff, gbase, voff) do { _Pragma("unroll") for (int _i = 0; _i < 2; ++_i) \
;         __builtin_amdgcn_global_load_lds((const unsigned*)((const char*)(gbase) + (voff)[_i]), (LAS unsigned*)(lds + (bufoff) + ldsw + _i * 8192), 16, 0, 0); } while (0)
; template <class J>
; DI void gemm_phase(LAS unsigned char* lds, const J& job) {
;   const int tid = my_tid(), wid = __builtin_amdgcn_readfirstlane(tid >> 6), lane = tid & 63, wr = wid >> 2, wc = wid & 3, fr = lane & 15, fq = lane >> 4;
;   const int nt = job.nt;
;   unsigned voffA[2], voffB[2];
; #pragma unroll
;   for (int i = 0; i < 2; ++i) { int R, C; stage_rc(tid * 16 + i * 8192, R, C); const int Rb = job.brow_of(R);
;     voffA[i] = (unsigned)(R * job.lda + C) * 2u; voffB[i] = (unsigned)(Rb * job.ldb + C) * 2u; }
;   const size_t kstep = (size_t)(BK * 2);
;   const size_t hstepA = (size_t)HALF * job.lda * 2, hstepB = (size_t)job.bhalf_rows() * job.ldb * 2;
;   const unsigned ldsw = (unsigned)wid * 1024u;
;   const int aoff = lds_byte(wr * 64 + fr, fq * 8), boff = lds_byte(wc * 32 + fr, fq * 8);
;     ...
;   Unit cur, nxt; int ui = 0;
;   if (!job.next(0, cur)) return;
;   f32x4 acc[2][2][4][2];
; #pragma unroll
;   for (int a = 0; a < 2; ++a)
; #pragma unroll
;     for (int b = 0; b < 2; ++b)
; #pragma unroll
;       for (int m = 0; m < 4; ++m)
; #pragma unroll
;         for (int n = 0; n < 2; ++n) acc[a][b][m][n] = (f32x4){0.f, 0.f, 0.f, 0.f};
;   bf16x8 At[4][2], B0[2][2], B1[2][2];
;   const char* cA = job.aptr(cur); const char* cB = job.bptr(cur);
;   const int koff = (my_block() & 7) * (nt >> 3), kmask = nt - 1;
;     ...
;   G_STAGE(G_SB(0, 0), cB + G_KT(0), voffB); G_STAGE(G_SA(0, 0), cA + G_KT(0), voffA); G_STAGE(G_SB(0, 1), cB + hstepB + G_KT(0), voffB); G_STAGE(G_SA(0, 1), cA + hstepA + G_KT(0), voffA);
;   if (wr == 1) G_BAR;
;   G_WAIT_V(4); G_BAR;
;   G_STAGE(G_SB(1, 0), cB + G_KT(1), voffB); G_STAGE(G_SA(1, 0), cA + G_KT(1), voffA); G_STAGE(G_SB(1, 1), cB + hstepB + G_KT(1), voffB);
;   G_WAIT_V(6); G_BAR;
;   DI const char* aptr(const Unit& u) const { return (const char*)(y + (size_t)u.pm * 256 * DM + (u.pn >> 3) * 512); }
;   DI const char* bptr(const Unit& u) const { return (const char*)(wbT + (size_t)u.pn * 256 * 512); }
.LBB0_96:
	s_andn2_b64 vcc, exec, s[8:9]
	s_cbranch_vccnz .LBB0_109
	v_mov_b32_e32 v0, v144
	s_cmpk_gt_i32 s43, 0x81f
	v_readfirstlane_b32 s4, v0
	s_cbranch_scc1 .LBB0_109
	v_lshlrev_b32_e32 v1, 4, v0
	v_add_u32_e32 v2, 0x2000, v1
	v_ashrrev_i32_e32 v3, 31, v2
	v_lshrrev_b32_e32 v3, 22, v3
	v_add_u32_e32 v3, v2, v3
	v_ashrrev_i32_e32 v3, 10, v3
	s_waitcnt vmcnt(0)
	v_mul_i32_i24_e32 v4, 0x400, v3
	v_sub_u32_e32 v2, v2, v4
	v_writelane_b32 v255, s87, 22
	v_lshrrev_b32_e32 v4, 4, v2
	v_writelane_b32 v255, s36, 20
	v_bitop3_b32 v2, v4, v2, 32 bitop3:0x6c
	v_ashrrev_i32_e32 v4, 31, v2
	v_writelane_b32 v255, s37, 21
	v_lshrrev_b32_e32 v4, 26, v4
	v_readlane_b32 s0, v255, 14
	v_readlane_b32 s1, v255, 15
	v_add_u32_e32 v4, v2, v4
	v_lshlrev_b32_e32 v6, 3, v3
	s_and_b64 s[6:7], s[0:1], exec
	v_ashrrev_i32_e32 v5, 6, v4
	v_and_b32_e32 v6, -16, v6
	v_and_b32_e32 v4, 0xc0, v4
	s_cselect_b32 s0, 0x800000, 0
	v_add_u32_e32 v5, v5, v6
	v_sub_u32_e32 v2, v2, v4
	s_add_u32 s14, s52, s0
	v_lshrrev_b32_e32 v7, 2, v5
	v_lshlrev_b32_e32 v8, 1, v5
	v_lshlrev_b32_e32 v3, 5, v3
	v_ashrrev_i16_sdwa v2, v220, sext(v2) dst_sel:DWORD dst_unused:UNUSED_PAD src0_sel:DWORD src1_sel:BYTE_0
	s_addc_u32 s15, s53, 0
	v_and_b32_e32 v6, 0x3fffe3, v5
	v_and_b32_e32 v7, 4, v7
	v_and_b32_e32 v8, 24, v8
	v_and_b32_e32 v3, 32, v3
	v_bfe_i32 v2, v2, 0, 16
	s_ashr_i32 s0, s43, 31
	v_or3_b32 v6, v6, v7, v8
	v_add_lshl_u32 v2, v3, v2, 1
	s_lshr_b32 s0, s0, 29
	v_lshl_add_u32 v128, v6, 10, v2
	v_lshl_add_u32 v130, v5, 12, v2
	v_bfe_i32 v2, v0, 27, 1
	s_add_i32 s0, s43, s0
	s_ashr_i32 s5, s4, 6
	v_lshrrev_b32_e32 v2, 22, v2
	s_and_b32 s1, s0, -8
	s_ashr_i32 s6, s4, 8
	s_lshl_b32 s24, s5, 10
	v_add_u32_e32 v2, v1, v2
	s_sub_i32 s1, s43, s1
	v_and_b32_e32 v2, 0xfffffc00, v2
	s_cmp_lt_i32 s1, 0
	s_movk_i32 s7, 0x105
	v_sub_u32_e32 v1, v1, v2
	v_ashrrev_i32_e32 v3, 31, v0
	s_cselect_b32 s7, s7, 0x104
	v_lshrrev_b32_e32 v2, 4, v1
	v_lshrrev_b32_e32 v3, 26, v3
	s_mul_i32 s1, s7, s1
	s_ashr_i32 s0, s0, 3
	v_bitop3_b32 v2, v2, v1, 32 bitop3:0x6c
	v_ashrrev_i32_e32 v1, 31, v1
	v_add_u32_e32 v3, v0, v3
	s_add_i32 s0, s1, s0
	v_lshrrev_b32_e32 v1, 26, v1
	v_ashrrev_i32_e32 v3, 6, v3
	s_ashr_i32 s1, s0, 31
	v_add_u32_e32 v1, v2, v1
	v_lshlrev_b32_e32 v4, 3, v3
	s_lshr_b32 s1, s1, 24
	v_ashrrev_i32_e32 v1, 6, v1
	v_and_b32_e32 v4, -16, v4
	s_add_i32 s1, s0, s1
	v_add_u32_e32 v4, v1, v4
	v_mul_i32_i24_e32 v1, 64, v1
	s_ashr_i32 s1, s1, 8
	v_sub_u32_e32 v1, v2, v1
	s_lshl_b32 s7, s1, 3
	v_lshrrev_b32_e32 v6, 2, v4
	v_lshlrev_b32_e32 v7, 1, v4
	v_lshlrev_b32_e32 v3, 5, v3
	v_ashrrev_i16_sdwa v1, v220, sext(v1) dst_sel:DWORD dst_unused:UNUSED_PAD src0_sel:DWORD src1_sel:BYTE_0
	s_sub_i32 s8, 0x41, s7
	s_lshl_b32 s1, s1, 8
	v_and_b32_e32 v5, 0x3fffe3, v4
	v_and_b32_e32 v6, 4, v6
	v_and_b32_e32 v7, 24, v7
	v_and_b32_e32 v3, 32, v3
	v_bfe_i32 v1, v1, 0, 16
	s_min_u32 s12, s8, 8
	s_sub_i32 s0, s0, s1
	v_or3_b32 v5, v5, v6, v7
	v_add_lshl_u32 v1, v3, v1, 1
	s_sext_i32_i16 s1, s0
	v_cvt_f32_ubyte0_e32 v3, s12
	v_lshl_add_u32 v146, v5, 10, v1
	v_cvt_f32_i32_e32 v2, s1
	v_rcp_iflag_f32_e32 v5, v3
	v_lshl_add_u32 v132, v4, 12, v1
	s_ashr_i32 s1, s1, 30
	s_or_b32 s1, s1, 1
	v_mul_f32_e32 v1, v2, v5
	v_trunc_f32_e32 v1, v1
	v_fma_f32 v2, -v1, v3, v2
	v_cvt_i32_f32_e32 v1, v1
	v_cmp_ge_f32_e64 s[8:9], |v2|, v3
	s_and_b64 s[8:9], s[8:9], exec
	s_cselect_b32 s1, s1, 0
	v_readfirstlane_b32 s8, v1
	s_add_i32 s8, s8, s1
	s_mul_i32 s1, s8, s12
	s_sub_i32 s0, s0, s1
	s_sext_i32_i16 s46, s8
	s_sext_i32_i16 s0, s0
	s_add_i32 s22, s7, s0
	s_lshl_b32 s0, s46, 6
	s_ashr_i32 s23, s22, 31
	s_and_b32 s16, s0, 0xfffffe00
	s_bfe_i64 s[8:9], s[8:9], 0x100000
	s_lshl_b64 s[12:13], s[22:23], 20
	s_ashr_i32 s17, s16, 31
	s_lshl_b64 s[8:9], s[8:9], 18
	s_add_u32 s62, s14, s8
	s_mov_b32 s7, s2
	s_addc_u32 s63, s15, s9
	s_and_b32 s0, s7, 7
	s_lshl_b32 s23, s0, 7
	s_add_u32 s8, s62, s23
	s_addc_u32 s9, s63, 0
	s_add_i32 s25, s24, 0x100
	s_add_i32 m0, s25, 0x10000
	s_nop 0
	global_load_lds_dwordx4 v146, s[8:9]
	s_add_i32 m0, s25, 0x12000
	s_add_u32 s0, s10, s12
	global_load_lds_dwordx4 v128, s[8:9]
	s_addc_u32 s1, s11, s13
	s_lshl_b64 s[8:9], s[16:17], 1
	s_add_u32 s64, s0, s8
	s_addc_u32 s65, s1, s9
	s_add_u32 s12, s64, s23
	s_addc_u32 s13, s65, 0
	s_add_i32 s36, s25, 0x2000
	s_add_u32 s8, s62, 0x20000
	s_mov_b32 m0, s25
	s_addc_u32 s9, s63, 0
	global_load_lds_dwordx4 v132, s[12:13]
	s_mov_b32 m0, s36
	s_add_u32 s16, s8, s23
	global_load_lds_dwordx4 v130, s[12:13]
	s_addc_u32 s17, s9, 0
	s_add_i32 m0, s25, 0x14000
	s_nop 0
	global_load_lds_dwordx4 v146, s[16:17]
	s_add_i32 m0, s25, 0x16000
	s_add_u32 s12, s12, 0x80000
	s_addc_u32 s13, s13, 0
	s_add_i32 s37, s25, 0x4000
	global_load_lds_dwordx4 v128, s[16:17]
	s_mov_b32 m0, s37
	s_add_i32 s38, s25, 0x6000
	global_load_lds_dwordx4 v132, s[12:13]
	s_mov_b32 m0, s38
	s_setprio 1
	s_cmp_lg_u32 s6, 1
	global_load_lds_dwordx4 v130, s[12:13]
	s_cbranch_scc1 .LBB0_100
	s_barrier
	s_setprio 0

; DI int my_tid() { int t = threadIdx.x; asm volatile("" : "+v"(t)); return t; }
; DI int my_block() { int b = blockIdx.x; asm volatile("" : "+s"(b)); return b; }
; #define G_WAIT_V(n) asm volatile("s_waitcnt vmcnt(" #n ")" ::: "memory")
; #define G_BAR __builtin_amdgcn_s_barrier()
;   DI int brow_of(int R) const { return (R & ~31) + perm32(R & 31); }
; template <class J>
; DI void gemm_phase(LAS unsigned char* lds, const J& job) {
;   const int tid = my_tid(), wid = __builtin_amdgcn_readfirstlane(tid >> 6), lane = tid & 63, wr = wid >> 2, wc = wid & 3, fr = lane & 15, fq = lane >> 4;
;   const int nt = job.nt;
;   unsigned voffA[2], voffB[2];
; #pragma unroll
;   for (int i = 0; i < 2; ++i) { int R, C; stage_rc(tid * 16 + i * 8192, R, C); const int Rb = job.brow_of(R);
;     voffA[i] = (unsigned)(R * job.lda + C) * 2u; voffB[i] = (unsigned)(Rb * job.ldb + C) * 2u; }
;   const size_t kstep = (size_t)(BK * 2);
;   const size_t hstepA = (size_t)HALF * job.lda * 2, hstepB = (size_t)job.bhalf_rows() * job.ldb * 2;
;   const unsigned ldsw = (unsigned)wid * 1024u;
;   const int aoff = lds_byte(wr * 64 + fr, fq * 8), boff = lds_byte(wc * 32 + fr, fq * 8);
;     ...
;   Unit cur, nxt; int ui = 0;
;   if (!job.next(0, cur)) return;
;   f32x4 acc[2][2][4][2];
; #pragma unroll
;   for (int a = 0; a < 2; ++a)
; #pragma unroll
;     for (int b = 0; b < 2; ++b)
; #pragma unroll
;       for (int m = 0; m < 4; ++m)
; #pragma unroll
;         for (int n = 0; n < 2; ++n) acc[a][b][m][n] = (f32x4){0.f, 0.f, 0.f, 0.f};
;   bf16x8 At[4][2], B0[2][2], B1[2][2];
;   const char* cA = job.aptr(cur); const char* cB = job.bptr(cur);
;   const int koff = (my_block() & 7) * (nt >> 3), kmask = nt - 1;
;     ...
;   G_STAGE(G_SB(0, 0), cB + G_KT(0), voffB); G_STAGE(G_SA(0, 0), cA + G_KT(0), voffA); G_STAGE(G_SB(0, 1), cB + hstepB + G_KT(0), voffB); G_STAGE(G_SA(0, 1), cA + hstepA + G_KT(0), voffA);
;   if (wr == 1) G_BAR;
;   G_WAIT_V(4); G_BAR;
;   G_STAGE(G_SB(1, 0), cB + G_KT(1), voffB); G_STAGE(G_SA(1, 0), cA + G_KT(1), voffA); G_STAGE(G_SB(1, 1), cB + hstepB + G_KT(1), voffB);
;   G_WAIT_V(6); G_BAR;
; __global__ void __launch_bounds__(512, 2) mega(Params p_unused) {
;     ...
;         { JobProj j; j.nt = 32; j.lda = DM; j.ldb = DM; j.l = l; j.G = G; j.c = c; j.nunits = NPAN * 24;
;           j.h = h; j.winT = winT + (size_t)l * INW * DM; j.proj = pz; j.out = p.out;
.LBB0_274:
	v_readlane_b32 s0, v255, 14
	s_load_dwordx2 s[10:11], s[60:61], 0xc8
	v_readlane_b32 s1, v255, 15
	s_and_b64 s[6:7], s[0:1], exec
	s_cselect_b32 s0, 0x3800000, 0
	s_add_u32 s12, s50, s0
	s_addc_u32 s13, s51, 0
	s_andn2_b64 vcc, exec, s[16:17]
	s_cbranch_vccnz .LBB0_318
	v_bfe_i32 v3, v0, 27, 1
	v_lshlrev_b32_e32 v1, 4, v0
	v_lshrrev_b32_e32 v3, 22, v3
	v_add_u32_e32 v3, v1, v3
	v_and_b32_e32 v3, 0xfffffc00, v3
	v_ashrrev_i32_e32 v2, 31, v0
	v_sub_u32_e32 v3, v1, v3
	v_lshrrev_b32_e32 v2, 26, v2
	s_waitcnt vmcnt(0)
	v_lshrrev_b32_e32 v4, 4, v3
	v_add_u32_e32 v2, v0, v2
	v_bitop3_b32 v4, v4, v3, 32 bitop3:0x6c
	v_ashrrev_i32_e32 v3, 31, v3
	v_ashrrev_i32_e32 v2, 6, v2
	v_lshrrev_b32_e32 v3, 26, v3
	v_lshlrev_b32_e32 v5, 3, v2
	v_add_u32_e32 v3, v4, v3
	v_and_b32_e32 v5, -16, v5
	v_ashrrev_i32_e32 v3, 6, v3
	v_add_u32_e32 v5, v3, v5
	v_mul_i32_i24_e32 v3, 64, v3
	v_sub_u32_e32 v3, v4, v3
	v_lshlrev_b32_e32 v2, 5, v2
	v_ashrrev_i16_sdwa v3, v220, sext(v3) dst_sel:DWORD dst_unused:UNUSED_PAD src0_sel:DWORD src1_sel:BYTE_0
	v_lshlrev_b32_e32 v4, 1, v5
	v_lshrrev_b32_e32 v6, 2, v5
	v_and_b32_e32 v2, 32, v2
	v_bfe_i32 v3, v3, 0, 16
	v_and_b32_e32 v4, 24, v4
	v_and_b32_e32 v6, 4, v6
	v_and_b32_e32 v7, 0xfffe3, v5
	v_or3_b32 v4, v7, v6, v4
	v_add_lshl_u32 v2, v2, v3, 1
	v_add_u32_e32 v1, 0x2000, v1
	v_lshl_add_u32 v128, v5, 12, v2
	v_lshl_add_u32 v146, v4, 12, v2
	v_ashrrev_i32_e32 v2, 31, v1
	v_lshrrev_b32_e32 v2, 22, v2
	v_add_u32_e32 v2, v1, v2
	s_ashr_i32 s16, s4, 6
	s_ashr_i32 s9, s8, 31
	s_ashr_i32 s65, s64, 31
	s_ashr_i32 s6, s4, 8
	v_ashrrev_i32_e32 v2, 10, v2
	s_lshl_b32 s5, s16, 10
	s_lshl_b64 s[18:19], s[8:9], 20
	s_lshl_b64 s[14:15], s[64:65], 20
	v_mul_i32_i24_e32 v3, 0x400, v2
	s_add_u32 s66, s12, s14
	s_mov_b32 s7, s2
	v_sub_u32_e32 v1, v1, v3
	s_addc_u32 s67, s13, s15
	s_lshl_b32 s0, s7, 2
	v_lshrrev_b32_e32 v3, 4, v1
	s_and_b32 s0, s0, 28
	v_bitop3_b32 v1, v3, v1, 32 bitop3:0x6c
	s_lshl_b32 s14, s0, 7
	v_ashrrev_i32_e32 v4, 31, v1
	s_add_u32 s20, s66, s14
	v_lshrrev_b32_e32 v4, 26, v4
	s_addc_u32 s21, s67, 0
	s_add_i32 s15, s5, 0x100
	v_lshlrev_b32_e32 v3, 3, v2
	v_add_u32_e32 v4, v1, v4
	s_add_i32 m0, s15, 0x10000
	v_and_b32_e32 v3, -16, v3
	v_ashrrev_i32_e32 v5, 6, v4
	v_and_b32_e32 v4, 0xc0, v4
	global_load_lds_dwordx4 v146, s[20:21]
	s_add_i32 m0, s15, 0x12000
	v_add_u32_e32 v3, v5, v3
	v_sub_u32_e32 v1, v1, v4
	s_add_u32 s68, s58, s18
	v_lshlrev_b32_e32 v2, 5, v2
	v_ashrrev_i16_sdwa v1, v220, sext(v1) dst_sel:DWORD dst_unused:UNUSED_PAD src0_sel:DWORD src1_sel:BYTE_0
	v_lshlrev_b32_e32 v4, 1, v3
	v_lshrrev_b32_e32 v5, 2, v3
	s_addc_u32 s69, s59, s19
	v_and_b32_e32 v2, 32, v2
	v_bfe_i32 v1, v1, 0, 16
	v_and_b32_e32 v4, 24, v4
	v_and_b32_e32 v5, 4, v5
	v_and_b32_e32 v6, 0xfffe3, v3
	s_add_u32 s18, s68, s14
	v_or3_b32 v4, v6, v5, v4
	v_add_lshl_u32 v1, v2, v1, 1
	s_addc_u32 s19, s69, 0
	s_add_i32 s24, s15, 0x2000
	v_lshl_add_u32 v132, v4, 12, v1
	s_add_u32 s9, s66, 0x80000
	global_load_lds_dwordx4 v132, s[20:21]
	s_mov_b32 m0, s15
	s_addc_u32 s17, s67, 0
	v_lshl_add_u32 v130, v3, 12, v1
	global_load_lds_dwordx4 v128, s[18:19]
	s_mov_b32 m0, s24
	s_add_u32 s20, s9, s14
	global_load_lds_dwordx4 v130, s[18:19]
	s_addc_u32 s21, s17, 0
	s_add_i32 m0, s15, 0x14000
	v_writelane_b32 v255, s36, 20
	global_load_lds_dwordx4 v146, s[20:21]
	s_add_i32 m0, s15, 0x16000
	s_add_u32 s18, s18, 0x80000
	s_addc_u32 s19, s19, 0
	s_add_i32 s25, s15, 0x4000
	v_writelane_b32 v255, s37, 21
	global_load_lds_dwordx4 v132, s[20:21]
	s_mov_b32 m0, s25
	s_add_i32 s36, s15, 0x6000
	global_load_lds_dwordx4 v128, s[18:19]
	s_mov_b32 m0, s36
	s_setprio 1
	s_cmp_lg_u32 s6, 1
	global_load_lds_dwordx4 v130, s[18:19]
	s_cbranch_scc1 .LBB0_277
	s_barrier
	s_setprio 0
